# v90 + RWKV scanner v4 (read2 V/SC pairs, banked DPP butterfly, zero-padded SC row removes the bonus mask ops)
# speedup vs baseline: 1.0032x; 1.0032x over previous
.Lscan_entry:
	s_waitcnt vmcnt(0) lgkmcnt(0)
	v_and_b32_e32 v16, 7, v161
	v_lshrrev_b32_e32 v17, 3, v161
	v_lshlrev_b32_e32 v137, 5, v16
	v_lshlrev_b32_e32 v139, 3, v17
	v_lshrrev_b32_e32 v18, 1, v16
	v_and_b32_e32 v19, 1, v16
	v_lshlrev_b32_e32 v18, 8, v18
	v_lshlrev_b32_e32 v19, 2, v19
	v_add3_u32 v84, v139, v18, v19
	v_add_u32_e32 v84, 0x7000, v84
	v_add_u32_e32 v139, 0x5000, v139
	v_mov_b32_e32 v128, 0x8008
	v_mov_b32_e32 v129, 0x8000
	v_cndmask_b32_e64 v156, v128, v129, s[42:43]
	v_and_b32_e32 v128, 15, v161
	v_lshrrev_b32_e32 v129, 4, v161
	v_lshlrev_b32_e32 v128, 4, v128
	v_mul_u32_u24_e32 v129, 0x8200, v129
	v_add_u32_e32 v128, v128, v129
	v_add_u32_e32 v128, 0x8008, v128
	v_mov_b32_e32 v16, 0
	v_mov_b32_e32 v17, 0
	v_cmp_gt_u32_e32 vcc, 32, v161
	s_and_saveexec_b64 s[0:1], vcc
	ds_write_b64 v128, v[16:17]
	s_mov_b64 exec, s[0:1]
	v_mov_b32_e32 v0, 0
	v_mov_b32_e32 v1, 0
	v_mov_b32_e32 v2, 0
	v_mov_b32_e32 v3, 0
	v_mov_b32_e32 v4, 0
	v_mov_b32_e32 v5, 0
	v_mov_b32_e32 v6, 0
	v_mov_b32_e32 v7, 0
	v_mov_b32_e32 v8, 0
	v_mov_b32_e32 v9, 0
	v_mov_b32_e32 v10, 0
	v_mov_b32_e32 v11, 0
	v_mov_b32_e32 v12, 0
	v_mov_b32_e32 v13, 0
	v_mov_b32_e32 v14, 0
	v_mov_b32_e32 v15, 0
	s_mov_b32 s1, 0
	s_movk_i32 s2, 0x80
	s_waitcnt lgkmcnt(0)
	s_barrier

.Lscan_q4:
	s_waitcnt lgkmcnt(0)
	v_pk_mul_f32 v[16:17], v[2:3], v[34:35]
	v_pk_mul_f32 v[18:19], v[10:11], v[34:35]
	ds_read_b128 v[76:79], v130 offset:256
	v_pk_fma_f32 v[16:17], v[0:1], v[32:33], v[16:17]
	v_pk_fma_f32 v[18:19], v[8:9], v[32:33], v[18:19]
	ds_read_b128 v[80:83], v130 offset:272
	v_pk_fma_f32 v[16:17], v[4:5], v[36:37], v[16:17]
	v_pk_fma_f32 v[18:19], v[12:13], v[36:37], v[18:19]
	ds_read_b128 v[90:93], v130 offset:4352
	v_pk_fma_f32 v[16:17], v[6:7], v[38:39], v[16:17]
	v_pk_fma_f32 v[18:19], v[14:15], v[38:39], v[18:19]
	ds_read_b128 v[94:97], v130 offset:4368
	v_pk_mul_f32 v[20:21], v[2:3], v[42:43]
	v_add_f32_e32 v24, v16, v17
	ds_read_b128 v[112:115], v130 offset:12544
	v_add_f32_e32 v25, v18, v19
	v_pk_mul_f32 v[22:23], v[10:11], v[42:43]
	ds_read_b128 v[116:119], v130 offset:12560
	v_add_f32_dpp v24, v24, v24 quad_perm:[1,0,3,2] row_mask:0xf bank_mask:0xf bound_ctrl:1
	v_add_f32_dpp v25, v25, v25 quad_perm:[1,0,3,2] row_mask:0xf bank_mask:0xf bound_ctrl:1
	ds_read_b128 v[120:123], v130 offset:16640
	v_pk_fma_f32 v[20:21], v[0:1], v[40:41], v[20:21]
	v_add_f32_dpp v24, v24, v24 quad_perm:[2,3,0,1] row_mask:0xf bank_mask:0xf bound_ctrl:1
	ds_read_b128 v[124:127], v130 offset:16656
	v_add_f32_dpp v25, v25, v25 quad_perm:[2,3,0,1] row_mask:0xf bank_mask:0xf bound_ctrl:1
	v_pk_fma_f32 v[22:23], v[8:9], v[40:41], v[22:23]
	ds_read_b128 v[98:101], v130 offset:8448
	v_add_f32_dpp v24, v24, v24 row_half_mirror row_mask:0xf bank_mask:0xf bound_ctrl:1
	v_add_f32_dpp v25, v25, v25 row_half_mirror row_mask:0xf bank_mask:0xf bound_ctrl:1
	ds_read_b128 v[102:105], v130 offset:8464
	v_pk_fma_f32 v[20:21], v[4:5], v[44:45], v[20:21]
	v_pk_fma_f32 v[22:23], v[12:13], v[44:45], v[22:23]
	ds_read2_b64 v[106:109], v131 offset0:64 offset1:96
	v_pk_fma_f32 v[20:21], v[6:7], v[46:47], v[20:21]
	v_pk_fma_f32 v[22:23], v[14:15], v[46:47], v[22:23]
	ds_read2_b64 v[144:147], v85 offset0:4 offset1:6
	v_add_f32_e32 v26, v20, v21
	v_add_f32_e32 v27, v22, v23
	v_pk_fma_f32 v[176:177], v[24:25], v[140:141], v[26:27] op_sel_hi:[1,0,1]
	v_pk_mul_f32 v[164:165], v[56:57], v[24:25] op_sel_hi:[1,0]
	v_pk_mul_f32 v[166:167], v[56:57], v[24:25] op_sel:[0,1]
	v_pk_mul_f32 v[168:169], v[58:59], v[24:25] op_sel_hi:[1,0]
	v_pk_mul_f32 v[170:171], v[58:59], v[24:25] op_sel:[0,1]
	v_pk_fma_f32 v[164:165], v[64:65], v[72:73], v[164:165] op_sel_hi:[1,0,1]
	v_pk_fma_f32 v[166:167], v[64:65], v[72:73], v[166:167] op_sel:[0,1,0]
	v_pk_fma_f32 v[168:169], v[66:67], v[72:73], v[168:169] op_sel_hi:[1,0,1]
	v_pk_fma_f32 v[170:171], v[66:67], v[72:73], v[170:171] op_sel:[0,1,0]
	v_pk_fma_f32 v[0:1], v[0:1], v[48:49], v[164:165]
	v_pk_fma_f32 v[8:9], v[8:9], v[48:49], v[166:167]
	v_pk_fma_f32 v[2:3], v[2:3], v[50:51], v[168:169]
	v_pk_fma_f32 v[10:11], v[10:11], v[50:51], v[170:171]
	v_pk_mul_f32 v[164:165], v[60:61], v[24:25] op_sel_hi:[1,0]
	v_pk_mul_f32 v[166:167], v[60:61], v[24:25] op_sel:[0,1]
	v_pk_mul_f32 v[168:169], v[62:63], v[24:25] op_sel_hi:[1,0]
	v_pk_mul_f32 v[170:171], v[62:63], v[24:25] op_sel:[0,1]
	v_pk_fma_f32 v[164:165], v[68:69], v[72:73], v[164:165] op_sel_hi:[1,0,1]
	v_pk_fma_f32 v[166:167], v[68:69], v[72:73], v[166:167] op_sel:[0,1,0]
	v_pk_fma_f32 v[168:169], v[70:71], v[72:73], v[168:169] op_sel_hi:[1,0,1]
	v_pk_fma_f32 v[170:171], v[70:71], v[72:73], v[170:171] op_sel:[0,1,0]
	v_pk_fma_f32 v[4:5], v[4:5], v[52:53], v[164:165]
	v_pk_fma_f32 v[12:13], v[12:13], v[52:53], v[166:167]
	v_pk_fma_f32 v[6:7], v[6:7], v[54:55], v[168:169]
	v_pk_fma_f32 v[14:15], v[14:15], v[54:55], v[170:171]
	v_pk_fma_f32 v[176:177], v[72:73], v[140:141], v[176:177] op_sel:[0,1,0]
	s_waitcnt lgkmcnt(0)
	v_pk_mul_f32 v[16:17], v[2:3], v[78:79]
	v_pk_mul_f32 v[18:19], v[10:11], v[78:79]
	ds_read_b128 v[32:35], v130 offset:512
	v_pk_fma_f32 v[16:17], v[0:1], v[76:77], v[16:17]
	v_pk_fma_f32 v[18:19], v[8:9], v[76:77], v[18:19]
	ds_read_b128 v[36:39], v130 offset:528
	v_pk_fma_f32 v[16:17], v[4:5], v[80:81], v[16:17]
	v_pk_fma_f32 v[18:19], v[12:13], v[80:81], v[18:19]
	ds_read_b128 v[40:43], v130 offset:4608
	v_pk_fma_f32 v[16:17], v[6:7], v[82:83], v[16:17]
	v_pk_fma_f32 v[18:19], v[14:15], v[82:83], v[18:19]
	ds_read_b128 v[44:47], v130 offset:4624
	v_pk_mul_f32 v[20:21], v[2:3], v[92:93]
	v_add_f32_e32 v24, v16, v17
	ds_read_b128 v[56:59], v130 offset:12800
	v_add_f32_e32 v25, v18, v19
	v_pk_mul_f32 v[22:23], v[10:11], v[92:93]
	ds_read_b128 v[60:63], v130 offset:12816
	v_add_f32_dpp v24, v24, v24 quad_perm:[1,0,3,2] row_mask:0xf bank_mask:0xf bound_ctrl:1
	v_add_f32_dpp v25, v25, v25 quad_perm:[1,0,3,2] row_mask:0xf bank_mask:0xf bound_ctrl:1
	ds_read_b128 v[64:67], v130 offset:16896
	v_pk_fma_f32 v[20:21], v[0:1], v[90:91], v[20:21]
	v_add_f32_dpp v24, v24, v24 quad_perm:[2,3,0,1] row_mask:0xf bank_mask:0xf bound_ctrl:1
	ds_read_b128 v[68:71], v130 offset:16912
	v_add_f32_dpp v25, v25, v25 quad_perm:[2,3,0,1] row_mask:0xf bank_mask:0xf bound_ctrl:1
	v_pk_fma_f32 v[22:23], v[8:9], v[90:91], v[22:23]
	ds_read_b128 v[48:51], v130 offset:8704
	v_add_f32_dpp v24, v24, v24 row_half_mirror row_mask:0xf bank_mask:0xf bound_ctrl:1
	v_add_f32_dpp v25, v25, v25 row_half_mirror row_mask:0xf bank_mask:0xf bound_ctrl:1
	ds_read_b128 v[52:55], v130 offset:8720
	v_pk_fma_f32 v[20:21], v[4:5], v[94:95], v[20:21]
	v_pk_fma_f32 v[22:23], v[12:13], v[94:95], v[22:23]
	v_pk_fma_f32 v[20:21], v[6:7], v[96:97], v[20:21]
	v_pk_fma_f32 v[22:23], v[14:15], v[96:97], v[22:23]
	v_add_f32_e32 v26, v20, v21
	v_add_f32_e32 v27, v22, v23
	v_pk_fma_f32 v[178:179], v[24:25], v[142:143], v[26:27] op_sel_hi:[1,0,1]
	v_pk_mul_f32 v[164:165], v[112:113], v[24:25] op_sel_hi:[1,0]
	v_pk_mul_f32 v[166:167], v[112:113], v[24:25] op_sel:[0,1]
	v_pk_mul_f32 v[168:169], v[114:115], v[24:25] op_sel_hi:[1,0]
	v_pk_mul_f32 v[170:171], v[114:115], v[24:25] op_sel:[0,1]
	v_pk_fma_f32 v[164:165], v[120:121], v[74:75], v[164:165] op_sel_hi:[1,0,1]
	v_pk_fma_f32 v[166:167], v[120:121], v[74:75], v[166:167] op_sel:[0,1,0]
	v_pk_fma_f32 v[168:169], v[122:123], v[74:75], v[168:169] op_sel_hi:[1,0,1]
	v_pk_fma_f32 v[170:171], v[122:123], v[74:75], v[170:171] op_sel:[0,1,0]
	v_pk_fma_f32 v[0:1], v[0:1], v[98:99], v[164:165]
	v_pk_fma_f32 v[8:9], v[8:9], v[98:99], v[166:167]
	v_pk_fma_f32 v[2:3], v[2:3], v[100:101], v[168:169]
	v_pk_fma_f32 v[10:11], v[10:11], v[100:101], v[170:171]
	v_pk_mul_f32 v[164:165], v[116:117], v[24:25] op_sel_hi:[1,0]
	v_pk_mul_f32 v[166:167], v[116:117], v[24:25] op_sel:[0,1]
	v_pk_mul_f32 v[168:169], v[118:119], v[24:25] op_sel_hi:[1,0]
	v_pk_mul_f32 v[170:171], v[118:119], v[24:25] op_sel:[0,1]
	v_pk_fma_f32 v[164:165], v[124:125], v[74:75], v[164:165] op_sel_hi:[1,0,1]
	v_pk_fma_f32 v[166:167], v[124:125], v[74:75], v[166:167] op_sel:[0,1,0]
	v_pk_fma_f32 v[168:169], v[126:127], v[74:75], v[168:169] op_sel_hi:[1,0,1]
	v_pk_fma_f32 v[170:171], v[126:127], v[74:75], v[170:171] op_sel:[0,1,0]
	v_pk_fma_f32 v[4:5], v[4:5], v[102:103], v[164:165]
	v_pk_fma_f32 v[12:13], v[12:13], v[102:103], v[166:167]
	v_pk_fma_f32 v[6:7], v[6:7], v[104:105], v[168:169]
	v_pk_fma_f32 v[14:15], v[14:15], v[104:105], v[170:171]
	v_pk_fma_f32 v[178:179], v[74:75], v[142:143], v[178:179] op_sel:[0,1,0]
	s_waitcnt lgkmcnt(0)
	v_pk_mul_f32 v[16:17], v[2:3], v[34:35]
	v_pk_mul_f32 v[18:19], v[10:11], v[34:35]
	ds_read_b128 v[76:79], v130 offset:768
	v_pk_fma_f32 v[16:17], v[0:1], v[32:33], v[16:17]
	v_pk_fma_f32 v[18:19], v[8:9], v[32:33], v[18:19]
	ds_read_b128 v[80:83], v130 offset:784
	v_pk_fma_f32 v[16:17], v[4:5], v[36:37], v[16:17]
	v_pk_fma_f32 v[18:19], v[12:13], v[36:37], v[18:19]
	ds_read_b128 v[90:93], v130 offset:4864
	v_pk_fma_f32 v[16:17], v[6:7], v[38:39], v[16:17]
	v_pk_fma_f32 v[18:19], v[14:15], v[38:39], v[18:19]
	ds_read_b128 v[94:97], v130 offset:4880
	v_pk_mul_f32 v[20:21], v[2:3], v[42:43]
	v_add_f32_e32 v24, v16, v17
	ds_read_b128 v[112:115], v130 offset:13056
	v_add_f32_e32 v25, v18, v19
	v_pk_mul_f32 v[22:23], v[10:11], v[42:43]
	ds_read_b128 v[116:119], v130 offset:13072
	v_add_f32_dpp v24, v24, v24 quad_perm:[1,0,3,2] row_mask:0xf bank_mask:0xf bound_ctrl:1
	v_add_f32_dpp v25, v25, v25 quad_perm:[1,0,3,2] row_mask:0xf bank_mask:0xf bound_ctrl:1
	ds_read_b128 v[120:123], v130 offset:17152
	v_pk_fma_f32 v[20:21], v[0:1], v[40:41], v[20:21]
	v_add_f32_dpp v24, v24, v24 quad_perm:[2,3,0,1] row_mask:0xf bank_mask:0xf bound_ctrl:1
	ds_read_b128 v[124:127], v130 offset:17168
	v_add_f32_dpp v25, v25, v25 quad_perm:[2,3,0,1] row_mask:0xf bank_mask:0xf bound_ctrl:1
	v_pk_fma_f32 v[22:23], v[8:9], v[40:41], v[22:23]
	ds_read_b128 v[98:101], v130 offset:8960
	v_add_f32_dpp v24, v24, v24 row_half_mirror row_mask:0xf bank_mask:0xf bound_ctrl:1
	v_add_f32_dpp v25, v25, v25 row_half_mirror row_mask:0xf bank_mask:0xf bound_ctrl:1
	ds_read_b128 v[102:105], v130 offset:8976
	v_pk_fma_f32 v[20:21], v[4:5], v[44:45], v[20:21]
	v_pk_fma_f32 v[22:23], v[12:13], v[44:45], v[22:23]
	ds_read2_b64 v[72:75], v131 offset0:128 offset1:160
	v_pk_fma_f32 v[20:21], v[6:7], v[46:47], v[20:21]
	v_pk_fma_f32 v[22:23], v[14:15], v[46:47], v[22:23]
	ds_read2_b64 v[140:143], v85 offset0:8 offset1:10
	v_add_f32_e32 v26, v20, v21
	v_add_f32_e32 v27, v22, v23
	v_pk_fma_f32 v[180:181], v[24:25], v[144:145], v[26:27] op_sel_hi:[1,0,1]
	v_pk_mul_f32 v[164:165], v[56:57], v[24:25] op_sel_hi:[1,0]
	v_pk_mul_f32 v[166:167], v[56:57], v[24:25] op_sel:[0,1]
	v_pk_mul_f32 v[168:169], v[58:59], v[24:25] op_sel_hi:[1,0]
	v_pk_mul_f32 v[170:171], v[58:59], v[24:25] op_sel:[0,1]
	v_pk_fma_f32 v[164:165], v[64:65], v[106:107], v[164:165] op_sel_hi:[1,0,1]
	v_pk_fma_f32 v[166:167], v[64:65], v[106:107], v[166:167] op_sel:[0,1,0]
	v_pk_fma_f32 v[168:169], v[66:67], v[106:107], v[168:169] op_sel_hi:[1,0,1]
	v_pk_fma_f32 v[170:171], v[66:67], v[106:107], v[170:171] op_sel:[0,1,0]
	v_pk_fma_f32 v[0:1], v[0:1], v[48:49], v[164:165]
	v_pk_fma_f32 v[8:9], v[8:9], v[48:49], v[166:167]
	v_pk_fma_f32 v[2:3], v[2:3], v[50:51], v[168:169]
	v_pk_fma_f32 v[10:11], v[10:11], v[50:51], v[170:171]
	v_pk_mul_f32 v[164:165], v[60:61], v[24:25] op_sel_hi:[1,0]
	v_pk_mul_f32 v[166:167], v[60:61], v[24:25] op_sel:[0,1]
	v_pk_mul_f32 v[168:169], v[62:63], v[24:25] op_sel_hi:[1,0]
	v_pk_mul_f32 v[170:171], v[62:63], v[24:25] op_sel:[0,1]
	v_pk_fma_f32 v[164:165], v[68:69], v[106:107], v[164:165] op_sel_hi:[1,0,1]
	v_pk_fma_f32 v[166:167], v[68:69], v[106:107], v[166:167] op_sel:[0,1,0]
	v_pk_fma_f32 v[168:169], v[70:71], v[106:107], v[168:169] op_sel_hi:[1,0,1]
	v_pk_fma_f32 v[170:171], v[70:71], v[106:107], v[170:171] op_sel:[0,1,0]
	v_pk_fma_f32 v[4:5], v[4:5], v[52:53], v[164:165]
	v_pk_fma_f32 v[12:13], v[12:13], v[52:53], v[166:167]
	v_pk_fma_f32 v[6:7], v[6:7], v[54:55], v[168:169]
	v_pk_fma_f32 v[14:15], v[14:15], v[54:55], v[170:171]
	v_pk_fma_f32 v[180:181], v[106:107], v[144:145], v[180:181] op_sel:[0,1,0]
	s_waitcnt lgkmcnt(0)
	v_pk_mul_f32 v[16:17], v[2:3], v[78:79]
	v_pk_mul_f32 v[18:19], v[10:11], v[78:79]
	ds_read_b128 v[32:35], v130 offset:1024
	v_pk_fma_f32 v[16:17], v[0:1], v[76:77], v[16:17]
	v_pk_fma_f32 v[18:19], v[8:9], v[76:77], v[18:19]
	ds_read_b128 v[36:39], v130 offset:1040
	v_pk_fma_f32 v[16:17], v[4:5], v[80:81], v[16:17]
	v_pk_fma_f32 v[18:19], v[12:13], v[80:81], v[18:19]
	ds_read_b128 v[40:43], v130 offset:5120
	v_pk_fma_f32 v[16:17], v[6:7], v[82:83], v[16:17]
	v_pk_fma_f32 v[18:19], v[14:15], v[82:83], v[18:19]
	ds_read_b128 v[44:47], v130 offset:5136
	v_pk_mul_f32 v[20:21], v[2:3], v[92:93]
	v_add_f32_e32 v24, v16, v17
	ds_read_b128 v[56:59], v130 offset:13312
	v_add_f32_e32 v25, v18, v19
	v_pk_mul_f32 v[22:23], v[10:11], v[92:93]
	ds_read_b128 v[60:63], v130 offset:13328
	v_add_f32_dpp v24, v24, v24 quad_perm:[1,0,3,2] row_mask:0xf bank_mask:0xf bound_ctrl:1
	v_add_f32_dpp v25, v25, v25 quad_perm:[1,0,3,2] row_mask:0xf bank_mask:0xf bound_ctrl:1
	ds_read_b128 v[64:67], v130 offset:17408
	v_pk_fma_f32 v[20:21], v[0:1], v[90:91], v[20:21]
	v_add_f32_dpp v24, v24, v24 quad_perm:[2,3,0,1] row_mask:0xf bank_mask:0xf bound_ctrl:1
	ds_read_b128 v[68:71], v130 offset:17424
	v_add_f32_dpp v25, v25, v25 quad_perm:[2,3,0,1] row_mask:0xf bank_mask:0xf bound_ctrl:1
	v_pk_fma_f32 v[22:23], v[8:9], v[90:91], v[22:23]
	ds_read_b128 v[48:51], v130 offset:9216
	v_add_f32_dpp v24, v24, v24 row_half_mirror row_mask:0xf bank_mask:0xf bound_ctrl:1
	v_add_f32_dpp v25, v25, v25 row_half_mirror row_mask:0xf bank_mask:0xf bound_ctrl:1
	ds_read_b128 v[52:55], v130 offset:9232
	v_pk_fma_f32 v[20:21], v[4:5], v[94:95], v[20:21]
	v_pk_fma_f32 v[22:23], v[12:13], v[94:95], v[22:23]
	v_pk_fma_f32 v[20:21], v[6:7], v[96:97], v[20:21]
	v_pk_fma_f32 v[22:23], v[14:15], v[96:97], v[22:23]
	v_add_f32_e32 v26, v20, v21
	v_add_f32_e32 v27, v22, v23
	v_pk_fma_f32 v[182:183], v[24:25], v[146:147], v[26:27] op_sel_hi:[1,0,1]
	v_pk_mul_f32 v[164:165], v[112:113], v[24:25] op_sel_hi:[1,0]
	v_pk_mul_f32 v[166:167], v[112:113], v[24:25] op_sel:[0,1]
	v_pk_mul_f32 v[168:169], v[114:115], v[24:25] op_sel_hi:[1,0]
	v_pk_mul_f32 v[170:171], v[114:115], v[24:25] op_sel:[0,1]
	v_pk_fma_f32 v[164:165], v[120:121], v[108:109], v[164:165] op_sel_hi:[1,0,1]
	v_pk_fma_f32 v[166:167], v[120:121], v[108:109], v[166:167] op_sel:[0,1,0]
	v_pk_fma_f32 v[168:169], v[122:123], v[108:109], v[168:169] op_sel_hi:[1,0,1]
	v_pk_fma_f32 v[170:171], v[122:123], v[108:109], v[170:171] op_sel:[0,1,0]
	v_pk_fma_f32 v[0:1], v[0:1], v[98:99], v[164:165]
	v_pk_fma_f32 v[8:9], v[8:9], v[98:99], v[166:167]
	v_pk_fma_f32 v[2:3], v[2:3], v[100:101], v[168:169]
	v_pk_fma_f32 v[10:11], v[10:11], v[100:101], v[170:171]
	v_pk_mul_f32 v[164:165], v[116:117], v[24:25] op_sel_hi:[1,0]
	v_pk_mul_f32 v[166:167], v[116:117], v[24:25] op_sel:[0,1]
	v_pk_mul_f32 v[168:169], v[118:119], v[24:25] op_sel_hi:[1,0]
	v_pk_mul_f32 v[170:171], v[118:119], v[24:25] op_sel:[0,1]
	v_pk_fma_f32 v[164:165], v[124:125], v[108:109], v[164:165] op_sel_hi:[1,0,1]
	v_pk_fma_f32 v[166:167], v[124:125], v[108:109], v[166:167] op_sel:[0,1,0]
	v_pk_fma_f32 v[168:169], v[126:127], v[108:109], v[168:169] op_sel_hi:[1,0,1]
	v_pk_fma_f32 v[170:171], v[126:127], v[108:109], v[170:171] op_sel:[0,1,0]
	v_pk_fma_f32 v[4:5], v[4:5], v[102:103], v[164:165]
	v_pk_fma_f32 v[12:13], v[12:13], v[102:103], v[166:167]
	v_pk_fma_f32 v[6:7], v[6:7], v[104:105], v[168:169]
	v_pk_fma_f32 v[14:15], v[14:15], v[104:105], v[170:171]
	v_pk_fma_f32 v[182:183], v[108:109], v[146:147], v[182:183] op_sel:[0,1,0]
	v_add_f32_dpp v176, v176, v176 row_half_mirror row_mask:0xf bank_mask:0x5
	v_add_f32_dpp v176, v180, v180 row_half_mirror row_mask:0xf bank_mask:0xa
	v_add_f32_dpp v177, v177, v177 row_half_mirror row_mask:0xf bank_mask:0x5
	v_add_f32_dpp v177, v181, v181 row_half_mirror row_mask:0xf bank_mask:0xa
	v_add_f32_dpp v178, v178, v178 row_half_mirror row_mask:0xf bank_mask:0x5
	v_add_f32_dpp v178, v182, v182 row_half_mirror row_mask:0xf bank_mask:0xa
	v_add_f32_dpp v179, v179, v179 row_half_mirror row_mask:0xf bank_mask:0x5
	v_add_f32_dpp v179, v183, v183 row_half_mirror row_mask:0xf bank_mask:0xa
	v_cndmask_b32_e64 v16, v178, v176, s[46:47]
	v_cndmask_b32_e64 v17, v176, v178, s[46:47]
	v_cndmask_b32_e64 v18, v179, v177, s[46:47]
	v_cndmask_b32_e64 v19, v177, v179, s[46:47]
	v_add_u32_e32 v130, 0x400, v130
	v_add_f32_dpp v176, v17, v16 quad_perm:[2,3,0,1] row_mask:0xf bank_mask:0xf bound_ctrl:1
	v_add_u32_e32 v131, 0x400, v131
	v_add_f32_dpp v177, v19, v18 quad_perm:[2,3,0,1] row_mask:0xf bank_mask:0xf bound_ctrl:1
	v_add_u32_e32 v85, 64, v85
	v_cndmask_b32_e64 v16, v177, v176, s[48:49]
	v_cndmask_b32_e64 v17, v176, v177, s[48:49]
	s_add_i32 s0, s0, -1
	s_cmp_lg_u32 s0, 0
	v_add_f32_dpp v18, v17, v16 quad_perm:[1,0,3,2] row_mask:0xf bank_mask:0xf bound_ctrl:1
	s_nop 0
	ds_write_b32 v86, v18
	v_add_u32_e32 v86, 0x400, v86
	s_cbranch_scc1 .Lscan_q4
	s_xor_b32 s1, s1, 0x8200
	s_add_i32 s2, s2, -1
	s_waitcnt lgkmcnt(0)
	s_barrier
	s_cmp_lg_u32 s2, 0
	s_cbranch_scc1 .Lscan_chunk
	s_branch .LBB0_627
